# G1/G3 peeled first K-iteration additionally leaves the previous unit's epilogue stores in flight: first two counted waits relaxed to vmcnt(8+stores), second one only for non-first units
# speedup vs baseline: 1.0046x; 1.0028x over previous
.LBB0_117:
	s_ashr_i32 s13, s12, 31
	s_lshl_b64 s[16:17], s[12:13], 19
	s_add_u32 s16, s30, s16
	s_addc_u32 s17, s31, s17
	s_and_b64 s[18:19], s[2:3], exec
	s_cselect_b32 s13, s17, s21
	s_cselect_b32 s37, s16, s20
	s_ashr_i32 s11, s10, 31
	s_lshl_b64 s[18:19], s[10:11], 19
	s_add_u32 s18, s28, s18
	s_addc_u32 s19, s29, s19
	s_and_b64 s[24:25], s[2:3], exec
	s_cselect_b32 s11, s19, s23
	s_cselect_b32 s38, s18, s22
	s_add_u32 s20, s20, 0x40080
	s_addc_u32 s21, s21, 0
	s_add_u32 s39, s22, 0x100
	s_addc_u32 s40, s23, 0
	s_mov_b32 s41, -2
	ds_read_b128 v[170:173], v162
	ds_read_b128 v[174:177], v162 offset:1024
	ds_read_b128 v[178:181], v162 offset:2048
	ds_read_b128 v[182:185], v162 offset:3072
	ds_read_b128 v[186:189], v163
	ds_read_b128 v[190:193], v163 offset:1024
	ds_read_b128 v[194:197], v163 offset:2048
	ds_read_b128 v[198:201], v163 offset:3072
	s_add_u32 s22, s20, 0xfffc0080
	s_addc_u32 s23, s21, -1
	s_cmp_eq_u32 s41, 12
	s_cselect_b32 s25, s13, s23
	s_cselect_b32 s24, s37, s22
	s_cselect_b32 s23, s11, s40
	s_cselect_b32 s22, s38, s39
	v_readfirstlane_b32 s42, v165
	v_lshl_add_u64 v[226:227], s[20:21], 0, v[136:137]
	s_mov_b32 m0, s42
	v_readfirstlane_b32 s42, v166
	ds_read_b128 v[202:205], v164
	ds_read_b128 v[206:209], v164 offset:1024
	ds_read_b128 v[210:213], v164 offset:2048
	ds_read_b128 v[214:217], v164 offset:3072
	ds_read_b128 v[218:221], v164 offset:4096
	ds_read_b128 v[222:225], v164 offset:5120
	ds_read_b128 v[230:233], v164 offset:6144
	ds_read_b128 v[234:237], v164 offset:7168
	global_load_lds_dwordx4 v[226:227], off
	v_lshl_add_u64 v[226:227], s[20:21], 0, v[138:139]
	s_mov_b32 m0, s42
	s_nop 0
	global_load_lds_dwordx4 v[226:227], off
	s_waitcnt vmcnt(24)
	s_waitcnt lgkmcnt(0)
	s_barrier
	s_setprio 1
	s_waitcnt lgkmcnt(0)
	v_mfma_f32_16x16x32_bf16 v[124:127], v[170:173], v[202:205], 0
	v_mfma_f32_16x16x32_bf16 v[120:123], v[178:181], v[202:205], 0
	v_mfma_f32_16x16x32_bf16 v[116:119], v[170:173], v[210:213], 0
	v_mfma_f32_16x16x32_bf16 v[108:111], v[178:181], v[210:213], 0
	v_mfma_f32_16x16x32_bf16 v[100:103], v[170:173], v[218:221], 0
	v_mfma_f32_16x16x32_bf16 v[92:95], v[178:181], v[218:221], 0
	v_mfma_f32_16x16x32_bf16 v[84:87], v[170:173], v[230:233], 0
	v_mfma_f32_16x16x32_bf16 v[76:79], v[178:181], v[230:233], 0
	v_mfma_f32_16x16x32_bf16 v[124:127], v[174:177], v[206:209], v[124:127]
	v_mfma_f32_16x16x32_bf16 v[120:123], v[182:185], v[206:209], v[120:123]
	v_mfma_f32_16x16x32_bf16 v[116:119], v[174:177], v[214:217], v[116:119]
	v_mfma_f32_16x16x32_bf16 v[108:111], v[182:185], v[214:217], v[108:111]
	v_mfma_f32_16x16x32_bf16 v[100:103], v[174:177], v[222:225], v[100:103]
	v_mfma_f32_16x16x32_bf16 v[92:95], v[182:185], v[222:225], v[92:95]
	v_mfma_f32_16x16x32_bf16 v[84:87], v[174:177], v[234:237], v[84:87]
	v_mfma_f32_16x16x32_bf16 v[76:79], v[182:185], v[234:237], v[76:79]
	s_setprio 0
	s_setprio 1
	v_mfma_f32_16x16x32_bf16 v[112:115], v[186:189], v[202:205], 0
	v_mfma_f32_16x16x32_bf16 v[104:107], v[194:197], v[202:205], 0
	v_mfma_f32_16x16x32_bf16 v[96:99], v[186:189], v[210:213], 0
	v_mfma_f32_16x16x32_bf16 v[88:91], v[194:197], v[210:213], 0
	v_mfma_f32_16x16x32_bf16 v[80:83], v[186:189], v[218:221], 0
	v_mfma_f32_16x16x32_bf16 v[72:75], v[194:197], v[218:221], 0
	v_mfma_f32_16x16x32_bf16 v[68:71], v[186:189], v[230:233], 0
	v_mfma_f32_16x16x32_bf16 v[64:67], v[194:197], v[230:233], 0
	v_mfma_f32_16x16x32_bf16 v[112:115], v[190:193], v[206:209], v[112:115]
	v_mfma_f32_16x16x32_bf16 v[104:107], v[198:201], v[206:209], v[104:107]
	v_mfma_f32_16x16x32_bf16 v[96:99], v[190:193], v[214:217], v[96:99]
	v_mfma_f32_16x16x32_bf16 v[88:91], v[198:201], v[214:217], v[88:91]
	v_mfma_f32_16x16x32_bf16 v[80:83], v[190:193], v[222:225], v[80:83]
	v_mfma_f32_16x16x32_bf16 v[72:75], v[198:201], v[222:225], v[72:75]
	v_mfma_f32_16x16x32_bf16 v[68:71], v[190:193], v[234:237], v[68:71]
	v_mfma_f32_16x16x32_bf16 v[64:67], v[198:201], v[234:237], v[64:67]
	s_setprio 0
	s_barrier
	v_readfirstlane_b32 s42, v146
	v_lshl_add_u64 v[226:227], s[22:23], 0, v[130:131]
	s_mov_b32 m0, s42
	v_readfirstlane_b32 s42, v147
	ds_read_b128 v[202:205], v164 offset:16384
	ds_read_b128 v[206:209], v164 offset:17408
	ds_read_b128 v[210:213], v164 offset:18432
	ds_read_b128 v[214:217], v164 offset:19456
	ds_read_b128 v[218:221], v164 offset:20480
	ds_read_b128 v[222:225], v164 offset:21504
	ds_read_b128 v[230:233], v164 offset:22528
	ds_read_b128 v[234:237], v164 offset:23552
	global_load_lds_dwordx4 v[226:227], off
	s_mov_b32 m0, s42
	s_add_u32 s42, s22, 0x40000
	v_lshl_add_u64 v[238:239], s[22:23], 0, v[134:135]
	s_addc_u32 s43, s23, 0
	v_readfirstlane_b32 s44, v148
	global_load_lds_dwordx4 v[238:239], off
	v_lshl_add_u64 v[240:241], s[42:43], 0, v[130:131]
	s_mov_b32 m0, s44
	v_lshl_add_u64 v[242:243], s[24:25], 0, v[132:133]
	global_load_lds_dwordx4 v[240:241], off
	v_lshl_add_u64 v[240:241], s[42:43], 0, v[134:135]
	v_readfirstlane_b32 s42, v149
	s_mov_b32 m0, s42
	v_readfirstlane_b32 s42, v150
	global_load_lds_dwordx4 v[240:241], off
	v_lshl_add_u64 v[240:241], s[24:25], 0, v[128:129]
	s_mov_b32 m0, s42
	v_readfirstlane_b32 s42, v151
	global_load_lds_dwordx4 v[240:241], off
	s_mov_b32 m0, s42
	s_nop 0
	global_load_lds_dwordx4 v[242:243], off
	s_waitcnt vmcnt(24)
	s_cmp_lg_u32 s15, 1
	s_cbranch_scc1 .Lpeel_nf_g1l0
	s_waitcnt vmcnt(8)
.Lpeel_nf_g1l0:
	s_waitcnt lgkmcnt(0)
	s_barrier
	s_setprio 1
	s_waitcnt lgkmcnt(0)
	v_mfma_f32_16x16x32_bf16 v[60:63], v[170:173], v[202:205], 0
	v_mfma_f32_16x16x32_bf16 v[56:59], v[178:181], v[202:205], 0
	v_mfma_f32_16x16x32_bf16 v[52:55], v[170:173], v[210:213], 0
	v_mfma_f32_16x16x32_bf16 v[44:47], v[178:181], v[210:213], 0
	v_mfma_f32_16x16x32_bf16 v[36:39], v[170:173], v[218:221], 0
	v_mfma_f32_16x16x32_bf16 v[28:31], v[178:181], v[218:221], 0
	v_mfma_f32_16x16x32_bf16 v[20:23], v[170:173], v[230:233], 0
	v_mfma_f32_16x16x32_bf16 v[12:15], v[178:181], v[230:233], 0
	v_mfma_f32_16x16x32_bf16 v[60:63], v[174:177], v[206:209], v[60:63]
	v_mfma_f32_16x16x32_bf16 v[56:59], v[182:185], v[206:209], v[56:59]
	v_mfma_f32_16x16x32_bf16 v[52:55], v[174:177], v[214:217], v[52:55]
	v_mfma_f32_16x16x32_bf16 v[44:47], v[182:185], v[214:217], v[44:47]
	v_mfma_f32_16x16x32_bf16 v[36:39], v[174:177], v[222:225], v[36:39]
	v_mfma_f32_16x16x32_bf16 v[28:31], v[182:185], v[222:225], v[28:31]
	v_mfma_f32_16x16x32_bf16 v[20:23], v[174:177], v[234:237], v[20:23]
	v_mfma_f32_16x16x32_bf16 v[12:15], v[182:185], v[234:237], v[12:15]
	s_setprio 0
	s_setprio 1
	v_mfma_f32_16x16x32_bf16 v[48:51], v[186:189], v[202:205], 0
	v_mfma_f32_16x16x32_bf16 v[40:43], v[194:197], v[202:205], 0
	v_mfma_f32_16x16x32_bf16 v[32:35], v[186:189], v[210:213], 0
	v_mfma_f32_16x16x32_bf16 v[24:27], v[194:197], v[210:213], 0
	v_mfma_f32_16x16x32_bf16 v[16:19], v[186:189], v[218:221], 0
	v_mfma_f32_16x16x32_bf16 v[8:11], v[194:197], v[218:221], 0
	v_mfma_f32_16x16x32_bf16 v[4:7], v[186:189], v[230:233], 0
	v_mfma_f32_16x16x32_bf16 v[0:3], v[194:197], v[230:233], 0
	v_mfma_f32_16x16x32_bf16 v[48:51], v[190:193], v[206:209], v[48:51]
	v_mfma_f32_16x16x32_bf16 v[40:43], v[198:201], v[206:209], v[40:43]
	v_mfma_f32_16x16x32_bf16 v[32:35], v[190:193], v[214:217], v[32:35]
	v_mfma_f32_16x16x32_bf16 v[24:27], v[198:201], v[214:217], v[24:27]
	v_mfma_f32_16x16x32_bf16 v[16:19], v[190:193], v[222:225], v[16:19]
	v_mfma_f32_16x16x32_bf16 v[8:11], v[198:201], v[222:225], v[8:11]
	v_mfma_f32_16x16x32_bf16 v[4:7], v[190:193], v[234:237], v[4:7]
	v_mfma_f32_16x16x32_bf16 v[0:3], v[198:201], v[234:237], v[0:3]
	s_setprio 0
	s_barrier
	ds_read_b128 v[170:173], v167
	ds_read_b128 v[174:177], v167 offset:1024
	ds_read_b128 v[178:181], v167 offset:2048
	ds_read_b128 v[182:185], v167 offset:3072
	ds_read_b128 v[186:189], v168
	ds_read_b128 v[190:193], v168 offset:1024
	ds_read_b128 v[194:197], v168 offset:2048
	ds_read_b128 v[198:201], v168 offset:3072
	s_add_u32 s24, s24, 0x40000
	s_addc_u32 s25, s25, 0
	v_readfirstlane_b32 s42, v152
	v_lshl_add_u64 v[244:245], s[24:25], 0, v[128:129]
	s_mov_b32 m0, s42
	ds_read_b128 v[202:205], v164 offset:32768
	ds_read_b128 v[206:209], v164 offset:33792
	ds_read_b128 v[210:213], v164 offset:34816
	ds_read_b128 v[214:217], v164 offset:35840
	ds_read_b128 v[218:221], v164 offset:36864
	ds_read_b128 v[222:225], v164 offset:37888
	ds_read_b128 v[230:233], v164 offset:38912
	ds_read_b128 v[234:237], v164 offset:39936
	global_load_lds_dwordx4 v[244:245], off
	v_lshl_add_u64 v[244:245], s[24:25], 0, v[132:133]
	v_readfirstlane_b32 s24, v153
	s_mov_b32 m0, s24
	s_nop 0
	global_load_lds_dwordx4 v[244:245], off
	s_waitcnt vmcnt(8)
	s_waitcnt lgkmcnt(0)
	s_barrier
	s_setprio 1
	s_waitcnt lgkmcnt(0)
	v_mfma_f32_16x16x32_bf16 v[124:127], v[170:173], v[202:205], v[124:127]
	v_mfma_f32_16x16x32_bf16 v[120:123], v[178:181], v[202:205], v[120:123]
	v_mfma_f32_16x16x32_bf16 v[116:119], v[170:173], v[210:213], v[116:119]
	v_mfma_f32_16x16x32_bf16 v[108:111], v[178:181], v[210:213], v[108:111]
	v_mfma_f32_16x16x32_bf16 v[100:103], v[170:173], v[218:221], v[100:103]
	v_mfma_f32_16x16x32_bf16 v[92:95], v[178:181], v[218:221], v[92:95]
	v_mfma_f32_16x16x32_bf16 v[84:87], v[170:173], v[230:233], v[84:87]
	v_mfma_f32_16x16x32_bf16 v[76:79], v[178:181], v[230:233], v[76:79]
	v_mfma_f32_16x16x32_bf16 v[124:127], v[174:177], v[206:209], v[124:127]
	v_mfma_f32_16x16x32_bf16 v[120:123], v[182:185], v[206:209], v[120:123]
	v_mfma_f32_16x16x32_bf16 v[116:119], v[174:177], v[214:217], v[116:119]
	v_mfma_f32_16x16x32_bf16 v[108:111], v[182:185], v[214:217], v[108:111]
	v_mfma_f32_16x16x32_bf16 v[100:103], v[174:177], v[222:225], v[100:103]
	v_mfma_f32_16x16x32_bf16 v[92:95], v[182:185], v[222:225], v[92:95]
	v_mfma_f32_16x16x32_bf16 v[84:87], v[174:177], v[234:237], v[84:87]
	v_mfma_f32_16x16x32_bf16 v[76:79], v[182:185], v[234:237], v[76:79]
	s_setprio 0
	s_setprio 1
	v_mfma_f32_16x16x32_bf16 v[112:115], v[186:189], v[202:205], v[112:115]
	v_mfma_f32_16x16x32_bf16 v[104:107], v[194:197], v[202:205], v[104:107]
	v_mfma_f32_16x16x32_bf16 v[96:99], v[186:189], v[210:213], v[96:99]
	v_mfma_f32_16x16x32_bf16 v[88:91], v[194:197], v[210:213], v[88:91]
	v_mfma_f32_16x16x32_bf16 v[80:83], v[186:189], v[218:221], v[80:83]
	v_mfma_f32_16x16x32_bf16 v[72:75], v[194:197], v[218:221], v[72:75]
	v_mfma_f32_16x16x32_bf16 v[68:71], v[186:189], v[230:233], v[68:71]
	v_mfma_f32_16x16x32_bf16 v[64:67], v[194:197], v[230:233], v[64:67]
	v_mfma_f32_16x16x32_bf16 v[112:115], v[190:193], v[206:209], v[112:115]
	v_mfma_f32_16x16x32_bf16 v[104:107], v[198:201], v[206:209], v[104:107]
	v_mfma_f32_16x16x32_bf16 v[96:99], v[190:193], v[214:217], v[96:99]
	v_mfma_f32_16x16x32_bf16 v[88:91], v[198:201], v[214:217], v[88:91]
	v_mfma_f32_16x16x32_bf16 v[80:83], v[190:193], v[222:225], v[80:83]
	v_mfma_f32_16x16x32_bf16 v[72:75], v[198:201], v[222:225], v[72:75]
	v_mfma_f32_16x16x32_bf16 v[68:71], v[190:193], v[234:237], v[68:71]
	v_mfma_f32_16x16x32_bf16 v[64:67], v[198:201], v[234:237], v[64:67]
	s_setprio 0
	s_barrier
	v_readfirstlane_b32 s24, v154
	v_lshl_add_u64 v[226:227], v[226:227], 0, s[6:7]
	s_mov_b32 m0, s24
	v_readfirstlane_b32 s24, v155
	s_add_u32 s22, s22, 0x40080
	ds_read_b128 v[202:205], v164 offset:49152
	ds_read_b128 v[206:209], v164 offset:50176
	ds_read_b128 v[210:213], v164 offset:51200
	ds_read_b128 v[214:217], v164 offset:52224
	ds_read_b128 v[218:221], v164 offset:53248
	ds_read_b128 v[222:225], v164 offset:54272
	ds_read_b128 v[230:233], v164 offset:55296
	ds_read_b128 v[234:237], v164 offset:56320
	global_load_lds_dwordx4 v[226:227], off
	v_lshl_add_u64 v[226:227], v[238:239], 0, s[6:7]
	s_mov_b32 m0, s24
	s_addc_u32 s23, s23, 0
	v_readfirstlane_b32 s24, v158
	global_load_lds_dwordx4 v[226:227], off
	v_lshl_add_u64 v[226:227], s[22:23], 0, v[130:131]
	s_mov_b32 m0, s24
	s_nop 0
	global_load_lds_dwordx4 v[226:227], off
	v_lshl_add_u64 v[226:227], s[22:23], 0, v[134:135]
	v_readfirstlane_b32 s22, v159
	s_mov_b32 m0, s22
	v_readfirstlane_b32 s22, v156
	global_load_lds_dwordx4 v[226:227], off
	v_lshl_add_u64 v[226:227], v[240:241], 0, s[6:7]
	s_mov_b32 m0, s22
	v_readfirstlane_b32 s22, v157
	global_load_lds_dwordx4 v[226:227], off
	v_lshl_add_u64 v[226:227], v[242:243], 0, s[6:7]
	s_mov_b32 m0, s22
	s_nop 0
	global_load_lds_dwordx4 v[226:227], off
	s_waitcnt vmcnt(8)
	s_waitcnt lgkmcnt(0)
	s_barrier
	s_setprio 1
	s_waitcnt lgkmcnt(0)
	v_mfma_f32_16x16x32_bf16 v[60:63], v[170:173], v[202:205], v[60:63]
	v_mfma_f32_16x16x32_bf16 v[56:59], v[178:181], v[202:205], v[56:59]
	v_mfma_f32_16x16x32_bf16 v[52:55], v[170:173], v[210:213], v[52:55]
	v_mfma_f32_16x16x32_bf16 v[44:47], v[178:181], v[210:213], v[44:47]
	v_mfma_f32_16x16x32_bf16 v[36:39], v[170:173], v[218:221], v[36:39]
	v_mfma_f32_16x16x32_bf16 v[28:31], v[178:181], v[218:221], v[28:31]
	v_mfma_f32_16x16x32_bf16 v[20:23], v[170:173], v[230:233], v[20:23]
	v_mfma_f32_16x16x32_bf16 v[12:15], v[178:181], v[230:233], v[12:15]
	v_mfma_f32_16x16x32_bf16 v[60:63], v[174:177], v[206:209], v[60:63]
	v_mfma_f32_16x16x32_bf16 v[56:59], v[182:185], v[206:209], v[56:59]
	v_mfma_f32_16x16x32_bf16 v[52:55], v[174:177], v[214:217], v[52:55]
	v_mfma_f32_16x16x32_bf16 v[44:47], v[182:185], v[214:217], v[44:47]
	v_mfma_f32_16x16x32_bf16 v[36:39], v[174:177], v[222:225], v[36:39]
	v_mfma_f32_16x16x32_bf16 v[28:31], v[182:185], v[222:225], v[28:31]
	v_mfma_f32_16x16x32_bf16 v[20:23], v[174:177], v[234:237], v[20:23]
	v_mfma_f32_16x16x32_bf16 v[12:15], v[182:185], v[234:237], v[12:15]
	s_setprio 0
	s_setprio 1
	v_mfma_f32_16x16x32_bf16 v[48:51], v[186:189], v[202:205], v[48:51]
	v_mfma_f32_16x16x32_bf16 v[40:43], v[194:197], v[202:205], v[40:43]
	v_mfma_f32_16x16x32_bf16 v[32:35], v[186:189], v[210:213], v[32:35]
	v_mfma_f32_16x16x32_bf16 v[24:27], v[194:197], v[210:213], v[24:27]
	v_mfma_f32_16x16x32_bf16 v[16:19], v[186:189], v[218:221], v[16:19]
	v_mfma_f32_16x16x32_bf16 v[8:11], v[194:197], v[218:221], v[8:11]
	v_mfma_f32_16x16x32_bf16 v[4:7], v[186:189], v[230:233], v[4:7]
	v_mfma_f32_16x16x32_bf16 v[0:3], v[194:197], v[230:233], v[0:3]
	v_mfma_f32_16x16x32_bf16 v[48:51], v[190:193], v[206:209], v[48:51]
	v_mfma_f32_16x16x32_bf16 v[40:43], v[198:201], v[206:209], v[40:43]
	v_mfma_f32_16x16x32_bf16 v[32:35], v[190:193], v[214:217], v[32:35]
	v_mfma_f32_16x16x32_bf16 v[24:27], v[198:201], v[214:217], v[24:27]
	v_mfma_f32_16x16x32_bf16 v[16:19], v[190:193], v[222:225], v[16:19]
	v_mfma_f32_16x16x32_bf16 v[8:11], v[198:201], v[222:225], v[8:11]
	v_mfma_f32_16x16x32_bf16 v[4:7], v[190:193], v[234:237], v[4:7]
	v_mfma_f32_16x16x32_bf16 v[0:3], v[198:201], v[234:237], v[0:3]
	s_setprio 0
	s_barrier
	s_add_i32 s41, s41, 2
	s_add_u32 s20, s20, 0x100
	s_addc_u32 s21, s21, 0
	s_add_u32 s39, s39, 0x100
	s_addc_u32 s40, s40, 0

.LBB0_1300:
	s_ashr_i32 s15, s14, 31
	s_lshl_b64 s[16:17], s[14:15], 19
	s_add_u32 s16, s31, s16
	s_addc_u32 s17, s33, s17
	s_and_b64 s[18:19], s[2:3], exec
	s_cselect_b32 s15, s17, s23
	s_cselect_b32 s38, s16, s22
	s_ashr_i32 s13, s12, 31
	s_lshl_b64 s[18:19], s[12:13], 19
	s_add_u32 s18, s29, s18
	s_addc_u32 s19, s30, s19
	s_and_b64 s[26:27], s[2:3], exec
	s_cselect_b32 s13, s19, s25
	s_cselect_b32 s39, s18, s24
	s_add_u32 s22, s22, 0x40080
	s_addc_u32 s23, s23, 0
	s_add_u32 s40, s24, 0x100
	s_addc_u32 s41, s25, 0
	s_mov_b32 s42, -2
	ds_read_b128 v[170:173], v163
	ds_read_b128 v[174:177], v163 offset:1024
	ds_read_b128 v[178:181], v163 offset:2048
	ds_read_b128 v[182:185], v163 offset:3072
	ds_read_b128 v[186:189], v164
	ds_read_b128 v[190:193], v164 offset:1024
	ds_read_b128 v[194:197], v164 offset:2048
	ds_read_b128 v[198:201], v164 offset:3072
	s_add_u32 s24, s22, 0xfffc0080
	s_addc_u32 s25, s23, -1
	s_cmp_eq_u32 s42, 12
	s_cselect_b32 s27, s15, s25
	s_cselect_b32 s26, s38, s24
	s_cselect_b32 s25, s13, s41
	s_cselect_b32 s24, s39, s40
	v_readfirstlane_b32 s43, v166
	v_lshl_add_u64 v[144:145], s[22:23], 0, v[136:137]
	s_mov_b32 m0, s43
	v_readfirstlane_b32 s43, v167
	ds_read_b128 v[202:205], v165
	ds_read_b128 v[206:209], v165 offset:1024
	ds_read_b128 v[210:213], v165 offset:2048
	ds_read_b128 v[214:217], v165 offset:3072
	ds_read_b128 v[218:221], v165 offset:4096
	ds_read_b128 v[222:225], v165 offset:5120
	ds_read_b128 v[230:233], v165 offset:6144
	ds_read_b128 v[234:237], v165 offset:7168
	global_load_lds_dwordx4 v[144:145], off
	v_lshl_add_u64 v[144:145], s[22:23], 0, v[138:139]
	s_mov_b32 m0, s43
	s_nop 0
	global_load_lds_dwordx4 v[144:145], off
	s_waitcnt vmcnt(16)
	s_waitcnt lgkmcnt(0)
	s_barrier
	s_setprio 1
	s_waitcnt lgkmcnt(0)
	v_mfma_f32_16x16x32_bf16 v[124:127], v[170:173], v[202:205], 0
	v_mfma_f32_16x16x32_bf16 v[120:123], v[178:181], v[202:205], 0
	v_mfma_f32_16x16x32_bf16 v[108:111], v[170:173], v[210:213], 0
	v_mfma_f32_16x16x32_bf16 v[104:107], v[178:181], v[210:213], 0
	v_mfma_f32_16x16x32_bf16 v[92:95], v[170:173], v[218:221], 0
	v_mfma_f32_16x16x32_bf16 v[88:91], v[178:181], v[218:221], 0
	v_mfma_f32_16x16x32_bf16 v[76:79], v[170:173], v[230:233], 0
	v_mfma_f32_16x16x32_bf16 v[72:75], v[178:181], v[230:233], 0
	v_mfma_f32_16x16x32_bf16 v[124:127], v[174:177], v[206:209], v[124:127]
	v_mfma_f32_16x16x32_bf16 v[120:123], v[182:185], v[206:209], v[120:123]
	v_mfma_f32_16x16x32_bf16 v[108:111], v[174:177], v[214:217], v[108:111]
	v_mfma_f32_16x16x32_bf16 v[104:107], v[182:185], v[214:217], v[104:107]
	v_mfma_f32_16x16x32_bf16 v[92:95], v[174:177], v[222:225], v[92:95]
	v_mfma_f32_16x16x32_bf16 v[88:91], v[182:185], v[222:225], v[88:91]
	v_mfma_f32_16x16x32_bf16 v[76:79], v[174:177], v[234:237], v[76:79]
	v_mfma_f32_16x16x32_bf16 v[72:75], v[182:185], v[234:237], v[72:75]
	s_setprio 0
	s_setprio 1
	v_mfma_f32_16x16x32_bf16 v[116:119], v[186:189], v[202:205], 0
	v_mfma_f32_16x16x32_bf16 v[112:115], v[194:197], v[202:205], 0
	v_mfma_f32_16x16x32_bf16 v[100:103], v[186:189], v[210:213], 0
	v_mfma_f32_16x16x32_bf16 v[96:99], v[194:197], v[210:213], 0
	v_mfma_f32_16x16x32_bf16 v[84:87], v[186:189], v[218:221], 0
	v_mfma_f32_16x16x32_bf16 v[80:83], v[194:197], v[218:221], 0
	v_mfma_f32_16x16x32_bf16 v[68:71], v[186:189], v[230:233], 0
	v_mfma_f32_16x16x32_bf16 v[64:67], v[194:197], v[230:233], 0
	v_mfma_f32_16x16x32_bf16 v[116:119], v[190:193], v[206:209], v[116:119]
	v_mfma_f32_16x16x32_bf16 v[112:115], v[198:201], v[206:209], v[112:115]
	v_mfma_f32_16x16x32_bf16 v[100:103], v[190:193], v[214:217], v[100:103]
	v_mfma_f32_16x16x32_bf16 v[96:99], v[198:201], v[214:217], v[96:99]
	v_mfma_f32_16x16x32_bf16 v[84:87], v[190:193], v[222:225], v[84:87]
	v_mfma_f32_16x16x32_bf16 v[80:83], v[198:201], v[222:225], v[80:83]
	v_mfma_f32_16x16x32_bf16 v[68:71], v[190:193], v[234:237], v[68:71]
	v_mfma_f32_16x16x32_bf16 v[64:67], v[198:201], v[234:237], v[64:67]
	s_setprio 0
	s_barrier
	v_readfirstlane_b32 s43, v147
	v_lshl_add_u64 v[144:145], s[24:25], 0, v[130:131]
	s_mov_b32 m0, s43
	v_readfirstlane_b32 s43, v148
	s_add_u32 s44, s24, 0x40000
	ds_read_b128 v[202:205], v165 offset:16384
	ds_read_b128 v[206:209], v165 offset:17408
	ds_read_b128 v[210:213], v165 offset:18432
	ds_read_b128 v[214:217], v165 offset:19456
	ds_read_b128 v[218:221], v165 offset:20480
	ds_read_b128 v[222:225], v165 offset:21504
	ds_read_b128 v[230:233], v165 offset:22528
	ds_read_b128 v[234:237], v165 offset:23552
	global_load_lds_dwordx4 v[144:145], off
	v_lshl_add_u64 v[226:227], s[24:25], 0, v[134:135]
	s_mov_b32 m0, s43
	s_addc_u32 s45, s25, 0
	v_readfirstlane_b32 s43, v149
	global_load_lds_dwordx4 v[226:227], off
	v_lshl_add_u64 v[238:239], s[44:45], 0, v[130:131]
	s_mov_b32 m0, s43
	v_readfirstlane_b32 s43, v150
	global_load_lds_dwordx4 v[238:239], off
	v_lshl_add_u64 v[238:239], s[44:45], 0, v[134:135]
	s_mov_b32 m0, s43
	v_readfirstlane_b32 s43, v151
	global_load_lds_dwordx4 v[238:239], off
	v_lshl_add_u64 v[238:239], s[26:27], 0, v[128:129]
	s_mov_b32 m0, s43
	v_readfirstlane_b32 s43, v152
	global_load_lds_dwordx4 v[238:239], off
	v_lshl_add_u64 v[240:241], s[26:27], 0, v[132:133]
	s_mov_b32 m0, s43
	s_nop 0
	global_load_lds_dwordx4 v[240:241], off
	s_waitcnt vmcnt(16)
	s_cmp_lg_u32 s21, 1
	s_cbranch_scc1 .Lpeel_nf_g3l0
	s_waitcnt vmcnt(8)
.Lpeel_nf_g3l0:
	s_waitcnt lgkmcnt(0)
	s_barrier
	s_setprio 1
	s_waitcnt lgkmcnt(0)
	v_mfma_f32_16x16x32_bf16 v[60:63], v[170:173], v[202:205], 0
	v_mfma_f32_16x16x32_bf16 v[56:59], v[178:181], v[202:205], 0
	v_mfma_f32_16x16x32_bf16 v[44:47], v[170:173], v[210:213], 0
	v_mfma_f32_16x16x32_bf16 v[40:43], v[178:181], v[210:213], 0
	v_mfma_f32_16x16x32_bf16 v[28:31], v[170:173], v[218:221], 0
	v_mfma_f32_16x16x32_bf16 v[24:27], v[178:181], v[218:221], 0
	v_mfma_f32_16x16x32_bf16 v[12:15], v[170:173], v[230:233], 0
	v_mfma_f32_16x16x32_bf16 v[8:11], v[178:181], v[230:233], 0
	v_mfma_f32_16x16x32_bf16 v[60:63], v[174:177], v[206:209], v[60:63]
	v_mfma_f32_16x16x32_bf16 v[56:59], v[182:185], v[206:209], v[56:59]
	v_mfma_f32_16x16x32_bf16 v[44:47], v[174:177], v[214:217], v[44:47]
	v_mfma_f32_16x16x32_bf16 v[40:43], v[182:185], v[214:217], v[40:43]
	v_mfma_f32_16x16x32_bf16 v[28:31], v[174:177], v[222:225], v[28:31]
	v_mfma_f32_16x16x32_bf16 v[24:27], v[182:185], v[222:225], v[24:27]
	v_mfma_f32_16x16x32_bf16 v[12:15], v[174:177], v[234:237], v[12:15]
	v_mfma_f32_16x16x32_bf16 v[8:11], v[182:185], v[234:237], v[8:11]
	s_setprio 0
	s_setprio 1
	v_mfma_f32_16x16x32_bf16 v[52:55], v[186:189], v[202:205], 0
	v_mfma_f32_16x16x32_bf16 v[48:51], v[194:197], v[202:205], 0
	v_mfma_f32_16x16x32_bf16 v[36:39], v[186:189], v[210:213], 0
	v_mfma_f32_16x16x32_bf16 v[32:35], v[194:197], v[210:213], 0
	v_mfma_f32_16x16x32_bf16 v[20:23], v[186:189], v[218:221], 0
	v_mfma_f32_16x16x32_bf16 v[16:19], v[194:197], v[218:221], 0
	v_mfma_f32_16x16x32_bf16 v[4:7], v[186:189], v[230:233], 0
	v_mfma_f32_16x16x32_bf16 v[0:3], v[194:197], v[230:233], 0
	v_mfma_f32_16x16x32_bf16 v[52:55], v[190:193], v[206:209], v[52:55]
	v_mfma_f32_16x16x32_bf16 v[48:51], v[198:201], v[206:209], v[48:51]
	v_mfma_f32_16x16x32_bf16 v[36:39], v[190:193], v[214:217], v[36:39]
	v_mfma_f32_16x16x32_bf16 v[32:35], v[198:201], v[214:217], v[32:35]
	v_mfma_f32_16x16x32_bf16 v[20:23], v[190:193], v[222:225], v[20:23]
	v_mfma_f32_16x16x32_bf16 v[16:19], v[198:201], v[222:225], v[16:19]
	v_mfma_f32_16x16x32_bf16 v[4:7], v[190:193], v[234:237], v[4:7]
	v_mfma_f32_16x16x32_bf16 v[0:3], v[198:201], v[234:237], v[0:3]
	s_setprio 0
	s_barrier
	ds_read_b128 v[170:173], v168
	ds_read_b128 v[174:177], v168 offset:1024
	ds_read_b128 v[178:181], v168 offset:2048
	ds_read_b128 v[182:185], v168 offset:3072
	ds_read_b128 v[186:189], v169
	ds_read_b128 v[190:193], v169 offset:1024
	ds_read_b128 v[194:197], v169 offset:2048
	ds_read_b128 v[198:201], v169 offset:3072
	s_add_u32 s26, s26, 0x40000
	s_addc_u32 s27, s27, 0
	v_readfirstlane_b32 s43, v153
	v_lshl_add_u64 v[242:243], s[26:27], 0, v[128:129]
	s_mov_b32 m0, s43
	ds_read_b128 v[202:205], v165 offset:32768
	ds_read_b128 v[206:209], v165 offset:33792
	ds_read_b128 v[210:213], v165 offset:34816
	ds_read_b128 v[214:217], v165 offset:35840
	ds_read_b128 v[218:221], v165 offset:36864
	ds_read_b128 v[222:225], v165 offset:37888
	ds_read_b128 v[230:233], v165 offset:38912
	ds_read_b128 v[234:237], v165 offset:39936
	global_load_lds_dwordx4 v[242:243], off
	v_lshl_add_u64 v[242:243], s[26:27], 0, v[132:133]
	v_readfirstlane_b32 s26, v154
	s_mov_b32 m0, s26
	s_nop 0
	global_load_lds_dwordx4 v[242:243], off
	s_waitcnt vmcnt(8)
	s_waitcnt lgkmcnt(0)
	s_barrier
	s_setprio 1
	s_waitcnt lgkmcnt(0)
	v_mfma_f32_16x16x32_bf16 v[124:127], v[170:173], v[202:205], v[124:127]
	v_mfma_f32_16x16x32_bf16 v[120:123], v[178:181], v[202:205], v[120:123]
	v_mfma_f32_16x16x32_bf16 v[108:111], v[170:173], v[210:213], v[108:111]
	v_mfma_f32_16x16x32_bf16 v[104:107], v[178:181], v[210:213], v[104:107]
	v_mfma_f32_16x16x32_bf16 v[92:95], v[170:173], v[218:221], v[92:95]
	v_mfma_f32_16x16x32_bf16 v[88:91], v[178:181], v[218:221], v[88:91]
	v_mfma_f32_16x16x32_bf16 v[76:79], v[170:173], v[230:233], v[76:79]
	v_mfma_f32_16x16x32_bf16 v[72:75], v[178:181], v[230:233], v[72:75]
	v_mfma_f32_16x16x32_bf16 v[124:127], v[174:177], v[206:209], v[124:127]
	v_mfma_f32_16x16x32_bf16 v[120:123], v[182:185], v[206:209], v[120:123]
	v_mfma_f32_16x16x32_bf16 v[108:111], v[174:177], v[214:217], v[108:111]
	v_mfma_f32_16x16x32_bf16 v[104:107], v[182:185], v[214:217], v[104:107]
	v_mfma_f32_16x16x32_bf16 v[92:95], v[174:177], v[222:225], v[92:95]
	v_mfma_f32_16x16x32_bf16 v[88:91], v[182:185], v[222:225], v[88:91]
	v_mfma_f32_16x16x32_bf16 v[76:79], v[174:177], v[234:237], v[76:79]
	v_mfma_f32_16x16x32_bf16 v[72:75], v[182:185], v[234:237], v[72:75]
	s_setprio 0
	s_setprio 1
	v_mfma_f32_16x16x32_bf16 v[116:119], v[186:189], v[202:205], v[116:119]
	v_mfma_f32_16x16x32_bf16 v[112:115], v[194:197], v[202:205], v[112:115]
	v_mfma_f32_16x16x32_bf16 v[100:103], v[186:189], v[210:213], v[100:103]
	v_mfma_f32_16x16x32_bf16 v[96:99], v[194:197], v[210:213], v[96:99]
	v_mfma_f32_16x16x32_bf16 v[84:87], v[186:189], v[218:221], v[84:87]
	v_mfma_f32_16x16x32_bf16 v[80:83], v[194:197], v[218:221], v[80:83]
	v_mfma_f32_16x16x32_bf16 v[68:71], v[186:189], v[230:233], v[68:71]
	v_mfma_f32_16x16x32_bf16 v[64:67], v[194:197], v[230:233], v[64:67]
	v_mfma_f32_16x16x32_bf16 v[116:119], v[190:193], v[206:209], v[116:119]
	v_mfma_f32_16x16x32_bf16 v[112:115], v[198:201], v[206:209], v[112:115]
	v_mfma_f32_16x16x32_bf16 v[100:103], v[190:193], v[214:217], v[100:103]
	v_mfma_f32_16x16x32_bf16 v[96:99], v[198:201], v[214:217], v[96:99]
	v_mfma_f32_16x16x32_bf16 v[84:87], v[190:193], v[222:225], v[84:87]
	v_mfma_f32_16x16x32_bf16 v[80:83], v[198:201], v[222:225], v[80:83]
	v_mfma_f32_16x16x32_bf16 v[68:71], v[190:193], v[234:237], v[68:71]
	v_mfma_f32_16x16x32_bf16 v[64:67], v[198:201], v[234:237], v[64:67]
	s_setprio 0
	s_barrier
	v_readfirstlane_b32 s26, v155
	v_lshl_add_u64 v[144:145], v[144:145], 0, s[6:7]
	s_mov_b32 m0, s26
	v_readfirstlane_b32 s26, v156
	s_add_u32 s24, s24, 0x40080
	ds_read_b128 v[202:205], v165 offset:49152
	ds_read_b128 v[206:209], v165 offset:50176
	ds_read_b128 v[210:213], v165 offset:51200
	ds_read_b128 v[214:217], v165 offset:52224
	ds_read_b128 v[218:221], v165 offset:53248
	ds_read_b128 v[222:225], v165 offset:54272
	ds_read_b128 v[230:233], v165 offset:55296
	ds_read_b128 v[234:237], v165 offset:56320
	global_load_lds_dwordx4 v[144:145], off
	v_lshl_add_u64 v[144:145], v[226:227], 0, s[6:7]
	s_mov_b32 m0, s26
	s_addc_u32 s25, s25, 0
	v_readfirstlane_b32 s26, v159
	global_load_lds_dwordx4 v[144:145], off
	v_lshl_add_u64 v[144:145], s[24:25], 0, v[130:131]
	s_mov_b32 m0, s26
	s_nop 0
	global_load_lds_dwordx4 v[144:145], off
	v_lshl_add_u64 v[144:145], s[24:25], 0, v[134:135]
	v_readfirstlane_b32 s24, v160
	s_mov_b32 m0, s24
	v_readfirstlane_b32 s24, v157
	global_load_lds_dwordx4 v[144:145], off
	v_lshl_add_u64 v[144:145], v[238:239], 0, s[6:7]
	s_mov_b32 m0, s24
	v_readfirstlane_b32 s24, v158
	global_load_lds_dwordx4 v[144:145], off
	v_lshl_add_u64 v[144:145], v[240:241], 0, s[6:7]
	s_mov_b32 m0, s24
	s_nop 0
	global_load_lds_dwordx4 v[144:145], off
	s_waitcnt vmcnt(8)
	s_waitcnt lgkmcnt(0)
	s_barrier
	s_setprio 1
	s_waitcnt lgkmcnt(0)
	v_mfma_f32_16x16x32_bf16 v[60:63], v[170:173], v[202:205], v[60:63]
	v_mfma_f32_16x16x32_bf16 v[56:59], v[178:181], v[202:205], v[56:59]
	v_mfma_f32_16x16x32_bf16 v[44:47], v[170:173], v[210:213], v[44:47]
	v_mfma_f32_16x16x32_bf16 v[40:43], v[178:181], v[210:213], v[40:43]
	v_mfma_f32_16x16x32_bf16 v[28:31], v[170:173], v[218:221], v[28:31]
	v_mfma_f32_16x16x32_bf16 v[24:27], v[178:181], v[218:221], v[24:27]
	v_mfma_f32_16x16x32_bf16 v[12:15], v[170:173], v[230:233], v[12:15]
	v_mfma_f32_16x16x32_bf16 v[8:11], v[178:181], v[230:233], v[8:11]
	v_mfma_f32_16x16x32_bf16 v[60:63], v[174:177], v[206:209], v[60:63]
	v_mfma_f32_16x16x32_bf16 v[56:59], v[182:185], v[206:209], v[56:59]
	v_mfma_f32_16x16x32_bf16 v[44:47], v[174:177], v[214:217], v[44:47]
	v_mfma_f32_16x16x32_bf16 v[40:43], v[182:185], v[214:217], v[40:43]
	v_mfma_f32_16x16x32_bf16 v[28:31], v[174:177], v[222:225], v[28:31]
	v_mfma_f32_16x16x32_bf16 v[24:27], v[182:185], v[222:225], v[24:27]
	v_mfma_f32_16x16x32_bf16 v[12:15], v[174:177], v[234:237], v[12:15]
	v_mfma_f32_16x16x32_bf16 v[8:11], v[182:185], v[234:237], v[8:11]
	s_setprio 0
	s_setprio 1
	v_mfma_f32_16x16x32_bf16 v[52:55], v[186:189], v[202:205], v[52:55]
	v_mfma_f32_16x16x32_bf16 v[48:51], v[194:197], v[202:205], v[48:51]
	v_mfma_f32_16x16x32_bf16 v[36:39], v[186:189], v[210:213], v[36:39]
	v_mfma_f32_16x16x32_bf16 v[32:35], v[194:197], v[210:213], v[32:35]
	v_mfma_f32_16x16x32_bf16 v[20:23], v[186:189], v[218:221], v[20:23]
	v_mfma_f32_16x16x32_bf16 v[16:19], v[194:197], v[218:221], v[16:19]
	v_mfma_f32_16x16x32_bf16 v[4:7], v[186:189], v[230:233], v[4:7]
	v_mfma_f32_16x16x32_bf16 v[0:3], v[194:197], v[230:233], v[0:3]
	v_mfma_f32_16x16x32_bf16 v[52:55], v[190:193], v[206:209], v[52:55]
	v_mfma_f32_16x16x32_bf16 v[48:51], v[198:201], v[206:209], v[48:51]
	v_mfma_f32_16x16x32_bf16 v[36:39], v[190:193], v[214:217], v[36:39]
	v_mfma_f32_16x16x32_bf16 v[32:35], v[198:201], v[214:217], v[32:35]
	v_mfma_f32_16x16x32_bf16 v[20:23], v[190:193], v[222:225], v[20:23]
	v_mfma_f32_16x16x32_bf16 v[16:19], v[198:201], v[222:225], v[16:19]
	v_mfma_f32_16x16x32_bf16 v[4:7], v[190:193], v[234:237], v[4:7]
	v_mfma_f32_16x16x32_bf16 v[0:3], v[198:201], v[234:237], v[0:3]
	s_setprio 0
	s_barrier
	s_add_i32 s42, s42, 2
	s_add_u32 s22, s22, 0x100
	s_addc_u32 s23, s23, 0
	s_add_u32 s40, s40, 0x100
	s_addc_u32 s41, s41, 0

.LBB0_1626:
	s_ashr_i32 s13, s12, 31
	s_lshl_b64 s[16:17], s[12:13], 19
	s_add_u32 s16, s30, s16
	s_addc_u32 s17, s31, s17
	s_and_b64 s[18:19], s[2:3], exec
	s_cselect_b32 s13, s17, s21
	s_cselect_b32 s37, s16, s20
	s_ashr_i32 s11, s10, 31
	s_lshl_b64 s[18:19], s[10:11], 19
	s_add_u32 s18, s28, s18
	s_addc_u32 s19, s29, s19
	s_and_b64 s[24:25], s[2:3], exec
	s_cselect_b32 s11, s19, s23
	s_cselect_b32 s38, s18, s22
	s_add_u32 s20, s20, 0x40080
	s_addc_u32 s21, s21, 0
	s_add_u32 s39, s22, 0x100
	s_addc_u32 s40, s23, 0
	s_mov_b32 s41, -2
	ds_read_b128 v[170:173], v162
	ds_read_b128 v[174:177], v162 offset:1024
	ds_read_b128 v[178:181], v162 offset:2048
	ds_read_b128 v[182:185], v162 offset:3072
	ds_read_b128 v[186:189], v163
	ds_read_b128 v[190:193], v163 offset:1024
	ds_read_b128 v[194:197], v163 offset:2048
	ds_read_b128 v[198:201], v163 offset:3072
	s_add_u32 s22, s20, 0xfffc0080
	s_addc_u32 s23, s21, -1
	s_cmp_eq_u32 s41, 12
	s_cselect_b32 s25, s13, s23
	s_cselect_b32 s24, s37, s22
	s_cselect_b32 s23, s11, s40
	s_cselect_b32 s22, s38, s39
	v_readfirstlane_b32 s42, v165
	v_lshl_add_u64 v[226:227], s[20:21], 0, v[136:137]
	s_mov_b32 m0, s42
	v_readfirstlane_b32 s42, v166
	ds_read_b128 v[202:205], v164
	ds_read_b128 v[206:209], v164 offset:1024
	ds_read_b128 v[210:213], v164 offset:2048
	ds_read_b128 v[214:217], v164 offset:3072
	ds_read_b128 v[218:221], v164 offset:4096
	ds_read_b128 v[222:225], v164 offset:5120
	ds_read_b128 v[230:233], v164 offset:6144
	ds_read_b128 v[234:237], v164 offset:7168
	global_load_lds_dwordx4 v[226:227], off
	v_lshl_add_u64 v[226:227], s[20:21], 0, v[138:139]
	s_mov_b32 m0, s42
	s_nop 0
	global_load_lds_dwordx4 v[226:227], off
	s_waitcnt vmcnt(24)
	s_waitcnt lgkmcnt(0)
	s_barrier
	s_setprio 1
	s_waitcnt lgkmcnt(0)
	v_mfma_f32_16x16x32_bf16 v[124:127], v[170:173], v[202:205], 0
	v_mfma_f32_16x16x32_bf16 v[120:123], v[178:181], v[202:205], 0
	v_mfma_f32_16x16x32_bf16 v[116:119], v[170:173], v[210:213], 0
	v_mfma_f32_16x16x32_bf16 v[108:111], v[178:181], v[210:213], 0
	v_mfma_f32_16x16x32_bf16 v[100:103], v[170:173], v[218:221], 0
	v_mfma_f32_16x16x32_bf16 v[92:95], v[178:181], v[218:221], 0
	v_mfma_f32_16x16x32_bf16 v[84:87], v[170:173], v[230:233], 0
	v_mfma_f32_16x16x32_bf16 v[76:79], v[178:181], v[230:233], 0
	v_mfma_f32_16x16x32_bf16 v[124:127], v[174:177], v[206:209], v[124:127]
	v_mfma_f32_16x16x32_bf16 v[120:123], v[182:185], v[206:209], v[120:123]
	v_mfma_f32_16x16x32_bf16 v[116:119], v[174:177], v[214:217], v[116:119]
	v_mfma_f32_16x16x32_bf16 v[108:111], v[182:185], v[214:217], v[108:111]
	v_mfma_f32_16x16x32_bf16 v[100:103], v[174:177], v[222:225], v[100:103]
	v_mfma_f32_16x16x32_bf16 v[92:95], v[182:185], v[222:225], v[92:95]
	v_mfma_f32_16x16x32_bf16 v[84:87], v[174:177], v[234:237], v[84:87]
	v_mfma_f32_16x16x32_bf16 v[76:79], v[182:185], v[234:237], v[76:79]
	s_setprio 0
	s_setprio 1
	v_mfma_f32_16x16x32_bf16 v[112:115], v[186:189], v[202:205], 0
	v_mfma_f32_16x16x32_bf16 v[104:107], v[194:197], v[202:205], 0
	v_mfma_f32_16x16x32_bf16 v[96:99], v[186:189], v[210:213], 0
	v_mfma_f32_16x16x32_bf16 v[88:91], v[194:197], v[210:213], 0
	v_mfma_f32_16x16x32_bf16 v[80:83], v[186:189], v[218:221], 0
	v_mfma_f32_16x16x32_bf16 v[72:75], v[194:197], v[218:221], 0
	v_mfma_f32_16x16x32_bf16 v[68:71], v[186:189], v[230:233], 0
	v_mfma_f32_16x16x32_bf16 v[64:67], v[194:197], v[230:233], 0
	v_mfma_f32_16x16x32_bf16 v[112:115], v[190:193], v[206:209], v[112:115]
	v_mfma_f32_16x16x32_bf16 v[104:107], v[198:201], v[206:209], v[104:107]
	v_mfma_f32_16x16x32_bf16 v[96:99], v[190:193], v[214:217], v[96:99]
	v_mfma_f32_16x16x32_bf16 v[88:91], v[198:201], v[214:217], v[88:91]
	v_mfma_f32_16x16x32_bf16 v[80:83], v[190:193], v[222:225], v[80:83]
	v_mfma_f32_16x16x32_bf16 v[72:75], v[198:201], v[222:225], v[72:75]
	v_mfma_f32_16x16x32_bf16 v[68:71], v[190:193], v[234:237], v[68:71]
	v_mfma_f32_16x16x32_bf16 v[64:67], v[198:201], v[234:237], v[64:67]
	s_setprio 0
	s_barrier
	v_readfirstlane_b32 s42, v146
	v_lshl_add_u64 v[226:227], s[22:23], 0, v[130:131]
	s_mov_b32 m0, s42
	v_readfirstlane_b32 s42, v147
	ds_read_b128 v[202:205], v164 offset:16384
	ds_read_b128 v[206:209], v164 offset:17408
	ds_read_b128 v[210:213], v164 offset:18432
	ds_read_b128 v[214:217], v164 offset:19456
	ds_read_b128 v[218:221], v164 offset:20480
	ds_read_b128 v[222:225], v164 offset:21504
	ds_read_b128 v[230:233], v164 offset:22528
	ds_read_b128 v[234:237], v164 offset:23552
	global_load_lds_dwordx4 v[226:227], off
	s_mov_b32 m0, s42
	s_add_u32 s42, s22, 0x40000
	v_lshl_add_u64 v[228:229], s[22:23], 0, v[134:135]
	s_addc_u32 s43, s23, 0
	v_readfirstlane_b32 s44, v148
	global_load_lds_dwordx4 v[228:229], off
	v_lshl_add_u64 v[238:239], s[42:43], 0, v[130:131]
	s_mov_b32 m0, s44
	v_lshl_add_u64 v[240:241], s[24:25], 0, v[132:133]
	global_load_lds_dwordx4 v[238:239], off
	v_lshl_add_u64 v[238:239], s[42:43], 0, v[134:135]
	v_readfirstlane_b32 s42, v149
	s_mov_b32 m0, s42
	v_readfirstlane_b32 s42, v150
	global_load_lds_dwordx4 v[238:239], off
	v_lshl_add_u64 v[238:239], s[24:25], 0, v[128:129]
	s_mov_b32 m0, s42
	v_readfirstlane_b32 s42, v151
	global_load_lds_dwordx4 v[238:239], off
	s_mov_b32 m0, s42
	s_nop 0
	global_load_lds_dwordx4 v[240:241], off
	s_waitcnt vmcnt(24)
	s_cmp_lg_u32 s15, 1
	s_cbranch_scc1 .Lpeel_nf_g1l1
	s_waitcnt vmcnt(8)
.Lpeel_nf_g1l1:
	s_waitcnt lgkmcnt(0)
	s_barrier
	s_setprio 1
	s_waitcnt lgkmcnt(0)
	v_mfma_f32_16x16x32_bf16 v[60:63], v[170:173], v[202:205], 0
	v_mfma_f32_16x16x32_bf16 v[56:59], v[178:181], v[202:205], 0
	v_mfma_f32_16x16x32_bf16 v[52:55], v[170:173], v[210:213], 0
	v_mfma_f32_16x16x32_bf16 v[44:47], v[178:181], v[210:213], 0
	v_mfma_f32_16x16x32_bf16 v[36:39], v[170:173], v[218:221], 0
	v_mfma_f32_16x16x32_bf16 v[28:31], v[178:181], v[218:221], 0
	v_mfma_f32_16x16x32_bf16 v[20:23], v[170:173], v[230:233], 0
	v_mfma_f32_16x16x32_bf16 v[12:15], v[178:181], v[230:233], 0
	v_mfma_f32_16x16x32_bf16 v[60:63], v[174:177], v[206:209], v[60:63]
	v_mfma_f32_16x16x32_bf16 v[56:59], v[182:185], v[206:209], v[56:59]
	v_mfma_f32_16x16x32_bf16 v[52:55], v[174:177], v[214:217], v[52:55]
	v_mfma_f32_16x16x32_bf16 v[44:47], v[182:185], v[214:217], v[44:47]
	v_mfma_f32_16x16x32_bf16 v[36:39], v[174:177], v[222:225], v[36:39]
	v_mfma_f32_16x16x32_bf16 v[28:31], v[182:185], v[222:225], v[28:31]
	v_mfma_f32_16x16x32_bf16 v[20:23], v[174:177], v[234:237], v[20:23]
	v_mfma_f32_16x16x32_bf16 v[12:15], v[182:185], v[234:237], v[12:15]
	s_setprio 0
	s_setprio 1
	v_mfma_f32_16x16x32_bf16 v[48:51], v[186:189], v[202:205], 0
	v_mfma_f32_16x16x32_bf16 v[40:43], v[194:197], v[202:205], 0
	v_mfma_f32_16x16x32_bf16 v[32:35], v[186:189], v[210:213], 0
	v_mfma_f32_16x16x32_bf16 v[24:27], v[194:197], v[210:213], 0
	v_mfma_f32_16x16x32_bf16 v[16:19], v[186:189], v[218:221], 0
	v_mfma_f32_16x16x32_bf16 v[8:11], v[194:197], v[218:221], 0
	v_mfma_f32_16x16x32_bf16 v[4:7], v[186:189], v[230:233], 0
	v_mfma_f32_16x16x32_bf16 v[0:3], v[194:197], v[230:233], 0
	v_mfma_f32_16x16x32_bf16 v[48:51], v[190:193], v[206:209], v[48:51]
	v_mfma_f32_16x16x32_bf16 v[40:43], v[198:201], v[206:209], v[40:43]
	v_mfma_f32_16x16x32_bf16 v[32:35], v[190:193], v[214:217], v[32:35]
	v_mfma_f32_16x16x32_bf16 v[24:27], v[198:201], v[214:217], v[24:27]
	v_mfma_f32_16x16x32_bf16 v[16:19], v[190:193], v[222:225], v[16:19]
	v_mfma_f32_16x16x32_bf16 v[8:11], v[198:201], v[222:225], v[8:11]
	v_mfma_f32_16x16x32_bf16 v[4:7], v[190:193], v[234:237], v[4:7]
	v_mfma_f32_16x16x32_bf16 v[0:3], v[198:201], v[234:237], v[0:3]
	s_setprio 0
	s_barrier
	ds_read_b128 v[170:173], v167
	ds_read_b128 v[174:177], v167 offset:1024
	ds_read_b128 v[178:181], v167 offset:2048
	ds_read_b128 v[182:185], v167 offset:3072
	ds_read_b128 v[186:189], v168
	ds_read_b128 v[190:193], v168 offset:1024
	ds_read_b128 v[194:197], v168 offset:2048
	ds_read_b128 v[198:201], v168 offset:3072
	s_add_u32 s24, s24, 0x40000
	s_addc_u32 s25, s25, 0
	v_readfirstlane_b32 s42, v152
	v_lshl_add_u64 v[242:243], s[24:25], 0, v[128:129]
	s_mov_b32 m0, s42
	ds_read_b128 v[202:205], v164 offset:32768
	ds_read_b128 v[206:209], v164 offset:33792
	ds_read_b128 v[210:213], v164 offset:34816
	ds_read_b128 v[214:217], v164 offset:35840
	ds_read_b128 v[218:221], v164 offset:36864
	ds_read_b128 v[222:225], v164 offset:37888
	ds_read_b128 v[230:233], v164 offset:38912
	ds_read_b128 v[234:237], v164 offset:39936
	global_load_lds_dwordx4 v[242:243], off
	v_lshl_add_u64 v[242:243], s[24:25], 0, v[132:133]
	v_readfirstlane_b32 s24, v153
	s_mov_b32 m0, s24
	s_nop 0
	global_load_lds_dwordx4 v[242:243], off
	s_waitcnt vmcnt(8)
	s_waitcnt lgkmcnt(0)
	s_barrier
	s_setprio 1
	s_waitcnt lgkmcnt(0)
	v_mfma_f32_16x16x32_bf16 v[124:127], v[170:173], v[202:205], v[124:127]
	v_mfma_f32_16x16x32_bf16 v[120:123], v[178:181], v[202:205], v[120:123]
	v_mfma_f32_16x16x32_bf16 v[116:119], v[170:173], v[210:213], v[116:119]
	v_mfma_f32_16x16x32_bf16 v[108:111], v[178:181], v[210:213], v[108:111]
	v_mfma_f32_16x16x32_bf16 v[100:103], v[170:173], v[218:221], v[100:103]
	v_mfma_f32_16x16x32_bf16 v[92:95], v[178:181], v[218:221], v[92:95]
	v_mfma_f32_16x16x32_bf16 v[84:87], v[170:173], v[230:233], v[84:87]
	v_mfma_f32_16x16x32_bf16 v[76:79], v[178:181], v[230:233], v[76:79]
	v_mfma_f32_16x16x32_bf16 v[124:127], v[174:177], v[206:209], v[124:127]
	v_mfma_f32_16x16x32_bf16 v[120:123], v[182:185], v[206:209], v[120:123]
	v_mfma_f32_16x16x32_bf16 v[116:119], v[174:177], v[214:217], v[116:119]
	v_mfma_f32_16x16x32_bf16 v[108:111], v[182:185], v[214:217], v[108:111]
	v_mfma_f32_16x16x32_bf16 v[100:103], v[174:177], v[222:225], v[100:103]
	v_mfma_f32_16x16x32_bf16 v[92:95], v[182:185], v[222:225], v[92:95]
	v_mfma_f32_16x16x32_bf16 v[84:87], v[174:177], v[234:237], v[84:87]
	v_mfma_f32_16x16x32_bf16 v[76:79], v[182:185], v[234:237], v[76:79]
	s_setprio 0
	s_setprio 1
	v_mfma_f32_16x16x32_bf16 v[112:115], v[186:189], v[202:205], v[112:115]
	v_mfma_f32_16x16x32_bf16 v[104:107], v[194:197], v[202:205], v[104:107]
	v_mfma_f32_16x16x32_bf16 v[96:99], v[186:189], v[210:213], v[96:99]
	v_mfma_f32_16x16x32_bf16 v[88:91], v[194:197], v[210:213], v[88:91]
	v_mfma_f32_16x16x32_bf16 v[80:83], v[186:189], v[218:221], v[80:83]
	v_mfma_f32_16x16x32_bf16 v[72:75], v[194:197], v[218:221], v[72:75]
	v_mfma_f32_16x16x32_bf16 v[68:71], v[186:189], v[230:233], v[68:71]
	v_mfma_f32_16x16x32_bf16 v[64:67], v[194:197], v[230:233], v[64:67]
	v_mfma_f32_16x16x32_bf16 v[112:115], v[190:193], v[206:209], v[112:115]
	v_mfma_f32_16x16x32_bf16 v[104:107], v[198:201], v[206:209], v[104:107]
	v_mfma_f32_16x16x32_bf16 v[96:99], v[190:193], v[214:217], v[96:99]
	v_mfma_f32_16x16x32_bf16 v[88:91], v[198:201], v[214:217], v[88:91]
	v_mfma_f32_16x16x32_bf16 v[80:83], v[190:193], v[222:225], v[80:83]
	v_mfma_f32_16x16x32_bf16 v[72:75], v[198:201], v[222:225], v[72:75]
	v_mfma_f32_16x16x32_bf16 v[68:71], v[190:193], v[234:237], v[68:71]
	v_mfma_f32_16x16x32_bf16 v[64:67], v[198:201], v[234:237], v[64:67]
	s_setprio 0
	s_barrier
	v_readfirstlane_b32 s24, v154
	v_lshl_add_u64 v[226:227], v[226:227], 0, s[6:7]
	s_mov_b32 m0, s24
	v_readfirstlane_b32 s24, v155
	s_add_u32 s22, s22, 0x40080
	ds_read_b128 v[202:205], v164 offset:49152
	ds_read_b128 v[206:209], v164 offset:50176
	ds_read_b128 v[210:213], v164 offset:51200
	ds_read_b128 v[214:217], v164 offset:52224
	ds_read_b128 v[218:221], v164 offset:53248
	ds_read_b128 v[222:225], v164 offset:54272
	ds_read_b128 v[230:233], v164 offset:55296
	ds_read_b128 v[234:237], v164 offset:56320
	global_load_lds_dwordx4 v[226:227], off
	v_lshl_add_u64 v[226:227], v[228:229], 0, s[6:7]
	s_mov_b32 m0, s24
	s_addc_u32 s23, s23, 0
	v_readfirstlane_b32 s24, v158
	global_load_lds_dwordx4 v[226:227], off
	v_lshl_add_u64 v[226:227], s[22:23], 0, v[130:131]
	s_mov_b32 m0, s24
	s_nop 0
	global_load_lds_dwordx4 v[226:227], off
	v_lshl_add_u64 v[226:227], s[22:23], 0, v[134:135]
	v_readfirstlane_b32 s22, v159
	s_mov_b32 m0, s22
	v_readfirstlane_b32 s22, v156
	global_load_lds_dwordx4 v[226:227], off
	v_lshl_add_u64 v[226:227], v[238:239], 0, s[6:7]
	s_mov_b32 m0, s22
	v_readfirstlane_b32 s22, v157
	global_load_lds_dwordx4 v[226:227], off
	v_lshl_add_u64 v[226:227], v[240:241], 0, s[6:7]
	s_mov_b32 m0, s22
	s_nop 0
	global_load_lds_dwordx4 v[226:227], off
	s_waitcnt vmcnt(8)
	s_waitcnt lgkmcnt(0)
	s_barrier
	s_setprio 1
	s_waitcnt lgkmcnt(0)
	v_mfma_f32_16x16x32_bf16 v[60:63], v[170:173], v[202:205], v[60:63]
	v_mfma_f32_16x16x32_bf16 v[56:59], v[178:181], v[202:205], v[56:59]
	v_mfma_f32_16x16x32_bf16 v[52:55], v[170:173], v[210:213], v[52:55]
	v_mfma_f32_16x16x32_bf16 v[44:47], v[178:181], v[210:213], v[44:47]
	v_mfma_f32_16x16x32_bf16 v[36:39], v[170:173], v[218:221], v[36:39]
	v_mfma_f32_16x16x32_bf16 v[28:31], v[178:181], v[218:221], v[28:31]
	v_mfma_f32_16x16x32_bf16 v[20:23], v[170:173], v[230:233], v[20:23]
	v_mfma_f32_16x16x32_bf16 v[12:15], v[178:181], v[230:233], v[12:15]
	v_mfma_f32_16x16x32_bf16 v[60:63], v[174:177], v[206:209], v[60:63]
	v_mfma_f32_16x16x32_bf16 v[56:59], v[182:185], v[206:209], v[56:59]
	v_mfma_f32_16x16x32_bf16 v[52:55], v[174:177], v[214:217], v[52:55]
	v_mfma_f32_16x16x32_bf16 v[44:47], v[182:185], v[214:217], v[44:47]
	v_mfma_f32_16x16x32_bf16 v[36:39], v[174:177], v[222:225], v[36:39]
	v_mfma_f32_16x16x32_bf16 v[28:31], v[182:185], v[222:225], v[28:31]
	v_mfma_f32_16x16x32_bf16 v[20:23], v[174:177], v[234:237], v[20:23]
	v_mfma_f32_16x16x32_bf16 v[12:15], v[182:185], v[234:237], v[12:15]
	s_setprio 0
	s_setprio 1
	v_mfma_f32_16x16x32_bf16 v[48:51], v[186:189], v[202:205], v[48:51]
	v_mfma_f32_16x16x32_bf16 v[40:43], v[194:197], v[202:205], v[40:43]
	v_mfma_f32_16x16x32_bf16 v[32:35], v[186:189], v[210:213], v[32:35]
	v_mfma_f32_16x16x32_bf16 v[24:27], v[194:197], v[210:213], v[24:27]
	v_mfma_f32_16x16x32_bf16 v[16:19], v[186:189], v[218:221], v[16:19]
	v_mfma_f32_16x16x32_bf16 v[8:11], v[194:197], v[218:221], v[8:11]
	v_mfma_f32_16x16x32_bf16 v[4:7], v[186:189], v[230:233], v[4:7]
	v_mfma_f32_16x16x32_bf16 v[0:3], v[194:197], v[230:233], v[0:3]
	v_mfma_f32_16x16x32_bf16 v[48:51], v[190:193], v[206:209], v[48:51]
	v_mfma_f32_16x16x32_bf16 v[40:43], v[198:201], v[206:209], v[40:43]
	v_mfma_f32_16x16x32_bf16 v[32:35], v[190:193], v[214:217], v[32:35]
	v_mfma_f32_16x16x32_bf16 v[24:27], v[198:201], v[214:217], v[24:27]
	v_mfma_f32_16x16x32_bf16 v[16:19], v[190:193], v[222:225], v[16:19]
	v_mfma_f32_16x16x32_bf16 v[8:11], v[198:201], v[222:225], v[8:11]
	v_mfma_f32_16x16x32_bf16 v[4:7], v[190:193], v[234:237], v[4:7]
	v_mfma_f32_16x16x32_bf16 v[0:3], v[198:201], v[234:237], v[0:3]
	s_setprio 0
	s_barrier
	s_add_i32 s41, s41, 2
	s_add_u32 s20, s20, 0x100
	s_addc_u32 s21, s21, 0
	s_add_u32 s39, s39, 0x100
	s_addc_u32 s40, s40, 0

.LBB0_2728:
	s_ashr_i32 s15, s14, 31
	s_lshl_b64 s[16:17], s[14:15], 19
	s_add_u32 s16, s31, s16
	s_addc_u32 s17, s33, s17
	s_and_b64 s[18:19], s[2:3], exec
	s_cselect_b32 s15, s17, s23
	s_cselect_b32 s38, s16, s22
	s_ashr_i32 s13, s12, 31
	s_lshl_b64 s[18:19], s[12:13], 19
	s_add_u32 s18, s29, s18
	s_addc_u32 s19, s30, s19
	s_and_b64 s[26:27], s[2:3], exec
	s_cselect_b32 s13, s19, s25
	s_cselect_b32 s39, s18, s24
	s_add_u32 s22, s22, 0x40080
	s_addc_u32 s23, s23, 0
	s_add_u32 s40, s24, 0x100
	s_addc_u32 s41, s25, 0
	s_mov_b32 s42, -2
	ds_read_b128 v[170:173], v163
	ds_read_b128 v[174:177], v163 offset:1024
	ds_read_b128 v[178:181], v163 offset:2048
	ds_read_b128 v[182:185], v163 offset:3072
	ds_read_b128 v[186:189], v164
	ds_read_b128 v[190:193], v164 offset:1024
	ds_read_b128 v[194:197], v164 offset:2048
	ds_read_b128 v[198:201], v164 offset:3072
	s_add_u32 s24, s22, 0xfffc0080
	s_addc_u32 s25, s23, -1
	s_cmp_eq_u32 s42, 12
	s_cselect_b32 s27, s15, s25
	s_cselect_b32 s26, s38, s24
	s_cselect_b32 s25, s13, s41
	s_cselect_b32 s24, s39, s40
	v_readfirstlane_b32 s43, v166
	v_lshl_add_u64 v[144:145], s[22:23], 0, v[136:137]
	s_mov_b32 m0, s43
	v_readfirstlane_b32 s43, v167
	ds_read_b128 v[202:205], v165
	ds_read_b128 v[206:209], v165 offset:1024
	ds_read_b128 v[210:213], v165 offset:2048
	ds_read_b128 v[214:217], v165 offset:3072
	ds_read_b128 v[218:221], v165 offset:4096
	ds_read_b128 v[222:225], v165 offset:5120
	ds_read_b128 v[230:233], v165 offset:6144
	ds_read_b128 v[234:237], v165 offset:7168
	global_load_lds_dwordx4 v[144:145], off
	v_lshl_add_u64 v[144:145], s[22:23], 0, v[138:139]
	s_mov_b32 m0, s43
	s_nop 0
	global_load_lds_dwordx4 v[144:145], off
	s_waitcnt vmcnt(16)
	s_waitcnt lgkmcnt(0)
	s_barrier
	s_setprio 1
	s_waitcnt lgkmcnt(0)
	v_mfma_f32_16x16x32_bf16 v[124:127], v[170:173], v[202:205], 0
	v_mfma_f32_16x16x32_bf16 v[120:123], v[178:181], v[202:205], 0
	v_mfma_f32_16x16x32_bf16 v[108:111], v[170:173], v[210:213], 0
	v_mfma_f32_16x16x32_bf16 v[104:107], v[178:181], v[210:213], 0
	v_mfma_f32_16x16x32_bf16 v[92:95], v[170:173], v[218:221], 0
	v_mfma_f32_16x16x32_bf16 v[88:91], v[178:181], v[218:221], 0
	v_mfma_f32_16x16x32_bf16 v[76:79], v[170:173], v[230:233], 0
	v_mfma_f32_16x16x32_bf16 v[72:75], v[178:181], v[230:233], 0
	v_mfma_f32_16x16x32_bf16 v[124:127], v[174:177], v[206:209], v[124:127]
	v_mfma_f32_16x16x32_bf16 v[120:123], v[182:185], v[206:209], v[120:123]
	v_mfma_f32_16x16x32_bf16 v[108:111], v[174:177], v[214:217], v[108:111]
	v_mfma_f32_16x16x32_bf16 v[104:107], v[182:185], v[214:217], v[104:107]
	v_mfma_f32_16x16x32_bf16 v[92:95], v[174:177], v[222:225], v[92:95]
	v_mfma_f32_16x16x32_bf16 v[88:91], v[182:185], v[222:225], v[88:91]
	v_mfma_f32_16x16x32_bf16 v[76:79], v[174:177], v[234:237], v[76:79]
	v_mfma_f32_16x16x32_bf16 v[72:75], v[182:185], v[234:237], v[72:75]
	s_setprio 0
	s_setprio 1
	v_mfma_f32_16x16x32_bf16 v[116:119], v[186:189], v[202:205], 0
	v_mfma_f32_16x16x32_bf16 v[112:115], v[194:197], v[202:205], 0
	v_mfma_f32_16x16x32_bf16 v[100:103], v[186:189], v[210:213], 0
	v_mfma_f32_16x16x32_bf16 v[96:99], v[194:197], v[210:213], 0
	v_mfma_f32_16x16x32_bf16 v[84:87], v[186:189], v[218:221], 0
	v_mfma_f32_16x16x32_bf16 v[80:83], v[194:197], v[218:221], 0
	v_mfma_f32_16x16x32_bf16 v[68:71], v[186:189], v[230:233], 0
	v_mfma_f32_16x16x32_bf16 v[64:67], v[194:197], v[230:233], 0
	v_mfma_f32_16x16x32_bf16 v[116:119], v[190:193], v[206:209], v[116:119]
	v_mfma_f32_16x16x32_bf16 v[112:115], v[198:201], v[206:209], v[112:115]
	v_mfma_f32_16x16x32_bf16 v[100:103], v[190:193], v[214:217], v[100:103]
	v_mfma_f32_16x16x32_bf16 v[96:99], v[198:201], v[214:217], v[96:99]
	v_mfma_f32_16x16x32_bf16 v[84:87], v[190:193], v[222:225], v[84:87]
	v_mfma_f32_16x16x32_bf16 v[80:83], v[198:201], v[222:225], v[80:83]
	v_mfma_f32_16x16x32_bf16 v[68:71], v[190:193], v[234:237], v[68:71]
	v_mfma_f32_16x16x32_bf16 v[64:67], v[198:201], v[234:237], v[64:67]
	s_setprio 0
	s_barrier
	v_readfirstlane_b32 s43, v147
	v_lshl_add_u64 v[144:145], s[24:25], 0, v[130:131]
	s_mov_b32 m0, s43
	v_readfirstlane_b32 s43, v148
	s_add_u32 s44, s24, 0x40000
	ds_read_b128 v[202:205], v165 offset:16384
	ds_read_b128 v[206:209], v165 offset:17408
	ds_read_b128 v[210:213], v165 offset:18432
	ds_read_b128 v[214:217], v165 offset:19456
	ds_read_b128 v[218:221], v165 offset:20480
	ds_read_b128 v[222:225], v165 offset:21504
	ds_read_b128 v[230:233], v165 offset:22528
	ds_read_b128 v[234:237], v165 offset:23552
	global_load_lds_dwordx4 v[144:145], off
	v_lshl_add_u64 v[226:227], s[24:25], 0, v[134:135]
	s_mov_b32 m0, s43
	s_addc_u32 s45, s25, 0
	v_readfirstlane_b32 s43, v149
	global_load_lds_dwordx4 v[226:227], off
	v_lshl_add_u64 v[228:229], s[44:45], 0, v[130:131]
	s_mov_b32 m0, s43
	v_readfirstlane_b32 s43, v150
	global_load_lds_dwordx4 v[228:229], off
	v_lshl_add_u64 v[228:229], s[44:45], 0, v[134:135]
	s_mov_b32 m0, s43
	v_readfirstlane_b32 s43, v151
	global_load_lds_dwordx4 v[228:229], off
	v_lshl_add_u64 v[228:229], s[26:27], 0, v[128:129]
	s_mov_b32 m0, s43
	v_readfirstlane_b32 s43, v152
	global_load_lds_dwordx4 v[228:229], off
	v_lshl_add_u64 v[238:239], s[26:27], 0, v[132:133]
	s_mov_b32 m0, s43
	s_nop 0
	global_load_lds_dwordx4 v[238:239], off
	s_waitcnt vmcnt(16)
	s_cmp_lg_u32 s21, 1
	s_cbranch_scc1 .Lpeel_nf_g3l1
	s_waitcnt vmcnt(8)
.Lpeel_nf_g3l1:
	s_waitcnt lgkmcnt(0)
	s_barrier
	s_setprio 1
	s_waitcnt lgkmcnt(0)
	v_mfma_f32_16x16x32_bf16 v[60:63], v[170:173], v[202:205], 0
	v_mfma_f32_16x16x32_bf16 v[56:59], v[178:181], v[202:205], 0
	v_mfma_f32_16x16x32_bf16 v[44:47], v[170:173], v[210:213], 0
	v_mfma_f32_16x16x32_bf16 v[40:43], v[178:181], v[210:213], 0
	v_mfma_f32_16x16x32_bf16 v[28:31], v[170:173], v[218:221], 0
	v_mfma_f32_16x16x32_bf16 v[24:27], v[178:181], v[218:221], 0
	v_mfma_f32_16x16x32_bf16 v[12:15], v[170:173], v[230:233], 0
	v_mfma_f32_16x16x32_bf16 v[8:11], v[178:181], v[230:233], 0
	v_mfma_f32_16x16x32_bf16 v[60:63], v[174:177], v[206:209], v[60:63]
	v_mfma_f32_16x16x32_bf16 v[56:59], v[182:185], v[206:209], v[56:59]
	v_mfma_f32_16x16x32_bf16 v[44:47], v[174:177], v[214:217], v[44:47]
	v_mfma_f32_16x16x32_bf16 v[40:43], v[182:185], v[214:217], v[40:43]
	v_mfma_f32_16x16x32_bf16 v[28:31], v[174:177], v[222:225], v[28:31]
	v_mfma_f32_16x16x32_bf16 v[24:27], v[182:185], v[222:225], v[24:27]
	v_mfma_f32_16x16x32_bf16 v[12:15], v[174:177], v[234:237], v[12:15]
	v_mfma_f32_16x16x32_bf16 v[8:11], v[182:185], v[234:237], v[8:11]
	s_setprio 0
	s_setprio 1
	v_mfma_f32_16x16x32_bf16 v[52:55], v[186:189], v[202:205], 0
	v_mfma_f32_16x16x32_bf16 v[48:51], v[194:197], v[202:205], 0
	v_mfma_f32_16x16x32_bf16 v[36:39], v[186:189], v[210:213], 0
	v_mfma_f32_16x16x32_bf16 v[32:35], v[194:197], v[210:213], 0
	v_mfma_f32_16x16x32_bf16 v[20:23], v[186:189], v[218:221], 0
	v_mfma_f32_16x16x32_bf16 v[16:19], v[194:197], v[218:221], 0
	v_mfma_f32_16x16x32_bf16 v[4:7], v[186:189], v[230:233], 0
	v_mfma_f32_16x16x32_bf16 v[0:3], v[194:197], v[230:233], 0
	v_mfma_f32_16x16x32_bf16 v[52:55], v[190:193], v[206:209], v[52:55]
	v_mfma_f32_16x16x32_bf16 v[48:51], v[198:201], v[206:209], v[48:51]
	v_mfma_f32_16x16x32_bf16 v[36:39], v[190:193], v[214:217], v[36:39]
	v_mfma_f32_16x16x32_bf16 v[32:35], v[198:201], v[214:217], v[32:35]
	v_mfma_f32_16x16x32_bf16 v[20:23], v[190:193], v[222:225], v[20:23]
	v_mfma_f32_16x16x32_bf16 v[16:19], v[198:201], v[222:225], v[16:19]
	v_mfma_f32_16x16x32_bf16 v[4:7], v[190:193], v[234:237], v[4:7]
	v_mfma_f32_16x16x32_bf16 v[0:3], v[198:201], v[234:237], v[0:3]
	s_setprio 0
	s_barrier
	ds_read_b128 v[170:173], v168
	ds_read_b128 v[174:177], v168 offset:1024
	ds_read_b128 v[178:181], v168 offset:2048
	ds_read_b128 v[182:185], v168 offset:3072
	ds_read_b128 v[186:189], v169
	ds_read_b128 v[190:193], v169 offset:1024
	ds_read_b128 v[194:197], v169 offset:2048
	ds_read_b128 v[198:201], v169 offset:3072
	s_add_u32 s26, s26, 0x40000
	s_addc_u32 s27, s27, 0
	v_readfirstlane_b32 s43, v153
	v_lshl_add_u64 v[240:241], s[26:27], 0, v[128:129]
	s_mov_b32 m0, s43
	ds_read_b128 v[202:205], v165 offset:32768
	ds_read_b128 v[206:209], v165 offset:33792
	ds_read_b128 v[210:213], v165 offset:34816
	ds_read_b128 v[214:217], v165 offset:35840
	ds_read_b128 v[218:221], v165 offset:36864
	ds_read_b128 v[222:225], v165 offset:37888
	ds_read_b128 v[230:233], v165 offset:38912
	ds_read_b128 v[234:237], v165 offset:39936
	global_load_lds_dwordx4 v[240:241], off
	v_lshl_add_u64 v[240:241], s[26:27], 0, v[132:133]
	v_readfirstlane_b32 s26, v154
	s_mov_b32 m0, s26
	s_nop 0
	global_load_lds_dwordx4 v[240:241], off
	s_waitcnt vmcnt(8)
	s_waitcnt lgkmcnt(0)
	s_barrier
	s_setprio 1
	s_waitcnt lgkmcnt(0)
	v_mfma_f32_16x16x32_bf16 v[124:127], v[170:173], v[202:205], v[124:127]
	v_mfma_f32_16x16x32_bf16 v[120:123], v[178:181], v[202:205], v[120:123]
	v_mfma_f32_16x16x32_bf16 v[108:111], v[170:173], v[210:213], v[108:111]
	v_mfma_f32_16x16x32_bf16 v[104:107], v[178:181], v[210:213], v[104:107]
	v_mfma_f32_16x16x32_bf16 v[92:95], v[170:173], v[218:221], v[92:95]
	v_mfma_f32_16x16x32_bf16 v[88:91], v[178:181], v[218:221], v[88:91]
	v_mfma_f32_16x16x32_bf16 v[76:79], v[170:173], v[230:233], v[76:79]
	v_mfma_f32_16x16x32_bf16 v[72:75], v[178:181], v[230:233], v[72:75]
	v_mfma_f32_16x16x32_bf16 v[124:127], v[174:177], v[206:209], v[124:127]
	v_mfma_f32_16x16x32_bf16 v[120:123], v[182:185], v[206:209], v[120:123]
	v_mfma_f32_16x16x32_bf16 v[108:111], v[174:177], v[214:217], v[108:111]
	v_mfma_f32_16x16x32_bf16 v[104:107], v[182:185], v[214:217], v[104:107]
	v_mfma_f32_16x16x32_bf16 v[92:95], v[174:177], v[222:225], v[92:95]
	v_mfma_f32_16x16x32_bf16 v[88:91], v[182:185], v[222:225], v[88:91]
	v_mfma_f32_16x16x32_bf16 v[76:79], v[174:177], v[234:237], v[76:79]
	v_mfma_f32_16x16x32_bf16 v[72:75], v[182:185], v[234:237], v[72:75]
	s_setprio 0
	s_setprio 1
	v_mfma_f32_16x16x32_bf16 v[116:119], v[186:189], v[202:205], v[116:119]
	v_mfma_f32_16x16x32_bf16 v[112:115], v[194:197], v[202:205], v[112:115]
	v_mfma_f32_16x16x32_bf16 v[100:103], v[186:189], v[210:213], v[100:103]
	v_mfma_f32_16x16x32_bf16 v[96:99], v[194:197], v[210:213], v[96:99]
	v_mfma_f32_16x16x32_bf16 v[84:87], v[186:189], v[218:221], v[84:87]
	v_mfma_f32_16x16x32_bf16 v[80:83], v[194:197], v[218:221], v[80:83]
	v_mfma_f32_16x16x32_bf16 v[68:71], v[186:189], v[230:233], v[68:71]
	v_mfma_f32_16x16x32_bf16 v[64:67], v[194:197], v[230:233], v[64:67]
	v_mfma_f32_16x16x32_bf16 v[116:119], v[190:193], v[206:209], v[116:119]
	v_mfma_f32_16x16x32_bf16 v[112:115], v[198:201], v[206:209], v[112:115]
	v_mfma_f32_16x16x32_bf16 v[100:103], v[190:193], v[214:217], v[100:103]
	v_mfma_f32_16x16x32_bf16 v[96:99], v[198:201], v[214:217], v[96:99]
	v_mfma_f32_16x16x32_bf16 v[84:87], v[190:193], v[222:225], v[84:87]
	v_mfma_f32_16x16x32_bf16 v[80:83], v[198:201], v[222:225], v[80:83]
	v_mfma_f32_16x16x32_bf16 v[68:71], v[190:193], v[234:237], v[68:71]
	v_mfma_f32_16x16x32_bf16 v[64:67], v[198:201], v[234:237], v[64:67]
	s_setprio 0
	s_barrier
	v_readfirstlane_b32 s26, v155
	v_lshl_add_u64 v[144:145], v[144:145], 0, s[6:7]
	s_mov_b32 m0, s26
	v_readfirstlane_b32 s26, v156
	s_add_u32 s24, s24, 0x40080
	ds_read_b128 v[202:205], v165 offset:49152
	ds_read_b128 v[206:209], v165 offset:50176
	ds_read_b128 v[210:213], v165 offset:51200
	ds_read_b128 v[214:217], v165 offset:52224
	ds_read_b128 v[218:221], v165 offset:53248
	ds_read_b128 v[222:225], v165 offset:54272
	ds_read_b128 v[230:233], v165 offset:55296
	ds_read_b128 v[234:237], v165 offset:56320
	global_load_lds_dwordx4 v[144:145], off
	v_lshl_add_u64 v[144:145], v[226:227], 0, s[6:7]
	s_mov_b32 m0, s26
	s_addc_u32 s25, s25, 0
	v_readfirstlane_b32 s26, v159
	global_load_lds_dwordx4 v[144:145], off
	v_lshl_add_u64 v[144:145], s[24:25], 0, v[130:131]
	s_mov_b32 m0, s26
	s_nop 0
	global_load_lds_dwordx4 v[144:145], off
	v_lshl_add_u64 v[144:145], s[24:25], 0, v[134:135]
	v_readfirstlane_b32 s24, v160
	s_mov_b32 m0, s24
	v_readfirstlane_b32 s24, v157
	global_load_lds_dwordx4 v[144:145], off
	v_lshl_add_u64 v[144:145], v[228:229], 0, s[6:7]
	s_mov_b32 m0, s24
	v_readfirstlane_b32 s24, v158
	global_load_lds_dwordx4 v[144:145], off
	v_lshl_add_u64 v[144:145], v[238:239], 0, s[6:7]
	s_mov_b32 m0, s24
	s_nop 0
	global_load_lds_dwordx4 v[144:145], off
	s_waitcnt vmcnt(8)
	s_waitcnt lgkmcnt(0)
	s_barrier
	s_setprio 1
	s_waitcnt lgkmcnt(0)
	v_mfma_f32_16x16x32_bf16 v[60:63], v[170:173], v[202:205], v[60:63]
	v_mfma_f32_16x16x32_bf16 v[56:59], v[178:181], v[202:205], v[56:59]
	v_mfma_f32_16x16x32_bf16 v[44:47], v[170:173], v[210:213], v[44:47]
	v_mfma_f32_16x16x32_bf16 v[40:43], v[178:181], v[210:213], v[40:43]
	v_mfma_f32_16x16x32_bf16 v[28:31], v[170:173], v[218:221], v[28:31]
	v_mfma_f32_16x16x32_bf16 v[24:27], v[178:181], v[218:221], v[24:27]
	v_mfma_f32_16x16x32_bf16 v[12:15], v[170:173], v[230:233], v[12:15]
	v_mfma_f32_16x16x32_bf16 v[8:11], v[178:181], v[230:233], v[8:11]
	v_mfma_f32_16x16x32_bf16 v[60:63], v[174:177], v[206:209], v[60:63]
	v_mfma_f32_16x16x32_bf16 v[56:59], v[182:185], v[206:209], v[56:59]
	v_mfma_f32_16x16x32_bf16 v[44:47], v[174:177], v[214:217], v[44:47]
	v_mfma_f32_16x16x32_bf16 v[40:43], v[182:185], v[214:217], v[40:43]
	v_mfma_f32_16x16x32_bf16 v[28:31], v[174:177], v[222:225], v[28:31]
	v_mfma_f32_16x16x32_bf16 v[24:27], v[182:185], v[222:225], v[24:27]
	v_mfma_f32_16x16x32_bf16 v[12:15], v[174:177], v[234:237], v[12:15]
	v_mfma_f32_16x16x32_bf16 v[8:11], v[182:185], v[234:237], v[8:11]
	s_setprio 0
	s_setprio 1
	v_mfma_f32_16x16x32_bf16 v[52:55], v[186:189], v[202:205], v[52:55]
	v_mfma_f32_16x16x32_bf16 v[48:51], v[194:197], v[202:205], v[48:51]
	v_mfma_f32_16x16x32_bf16 v[36:39], v[186:189], v[210:213], v[36:39]
	v_mfma_f32_16x16x32_bf16 v[32:35], v[194:197], v[210:213], v[32:35]
	v_mfma_f32_16x16x32_bf16 v[20:23], v[186:189], v[218:221], v[20:23]
	v_mfma_f32_16x16x32_bf16 v[16:19], v[194:197], v[218:221], v[16:19]
	v_mfma_f32_16x16x32_bf16 v[4:7], v[186:189], v[230:233], v[4:7]
	v_mfma_f32_16x16x32_bf16 v[0:3], v[194:197], v[230:233], v[0:3]
	v_mfma_f32_16x16x32_bf16 v[52:55], v[190:193], v[206:209], v[52:55]
	v_mfma_f32_16x16x32_bf16 v[48:51], v[198:201], v[206:209], v[48:51]
	v_mfma_f32_16x16x32_bf16 v[36:39], v[190:193], v[214:217], v[36:39]
	v_mfma_f32_16x16x32_bf16 v[32:35], v[198:201], v[214:217], v[32:35]
	v_mfma_f32_16x16x32_bf16 v[20:23], v[190:193], v[222:225], v[20:23]
	v_mfma_f32_16x16x32_bf16 v[16:19], v[198:201], v[222:225], v[16:19]
	v_mfma_f32_16x16x32_bf16 v[4:7], v[190:193], v[234:237], v[4:7]
	v_mfma_f32_16x16x32_bf16 v[0:3], v[198:201], v[234:237], v[0:3]
	s_setprio 0
	s_barrier
	s_add_i32 s42, s42, 2
	s_add_u32 s22, s22, 0x100
	s_addc_u32 s23, s23, 0
	s_add_u32 s40, s40, 0x100
	s_addc_u32 s41, s41, 0
